# MLA loop: per-phase setprio removed, O-rescale skipped when max unchanged, compiler pad nops after asm max3 removed (MLA+SWA), false dst-sel pad nops removed in RWKV loops
# speedup vs baseline: 1.0056x; 1.0056x over previous
; #define LAS __attribute__((address_space(3)))
; DEVI float dpp_xor1(float v) { return __int_as_float(__builtin_amdgcn_update_dpp(0, __float_as_int(v), 0xB1, 0xF, 0xF, false)); }
; DEVI float dpp_xor2(float v) { return __int_as_float(__builtin_amdgcn_update_dpp(0, __float_as_int(v), 0x4E, 0xF, 0xF, false)); }
; DEVI void rwkv_A(LAS unsigned char* lds, const Params& P) {
;     ...
;             for (int s = 0; s < RW_T; ++s) {
;                 const LAS unsigned char* sp = sb + s * RW_STEPB;
;                 f32x2 w[8], a[8], b[8], k[8];
; #pragma unroll
;                 for (int q = 0; q < 4; ++q) {
;                     const f32x4 tw = *(const LAS f32x4*)(sp + q * 16), ta = *(const LAS f32x4*)(sp + 256 + q * 16), tb_ = *(const LAS f32x4*)(sp + 512 + q * 16), tk = *(const LAS f32x4*)(sp + 768 + q * 16);
;                     w[2 * q] = (f32x2){tw[0], tw[1]}; w[2 * q + 1] = (f32x2){tw[2], tw[3]}; a[2 * q] = (f32x2){ta[0], ta[1]}; a[2 * q + 1] = (f32x2){ta[2], ta[3]};
;                     b[2 * q] = (f32x2){tb_[0], tb_[1]}; b[2 * q + 1] = (f32x2){tb_[2], tb_[3]}; k[2 * q] = (f32x2){tk[0], tk[1]}; k[2 * q + 1] = (f32x2){tk[2], tk[3]};
;                 }
;                 const LAS float* vp = (const LAS float*)(sp - qc * 64 + 1280 + rp * 8);
;                 const float vi[2] = {vp[0], vp[1]};
; #pragma unroll
;                 for (int h = 0; h < 2; ++h) {
;                     f32x2 ap = {0.f, 0.f}, au = {0.f, 0.f};
; #pragma unroll
;                     for (int j = 0; j < 8; ++j) { ap = __builtin_elementwise_fma(Pm[h][j], a[j], ap); au = __builtin_elementwise_fma(Um[h][j], a[j], au); }
;                     float sp_ = ap[0] + ap[1], su = au[0] + au[1];
;                     sp_ += dpp_xor1(sp_); su += dpp_xor1(su); sp_ += dpp_xor2(sp_); su += dpp_xor2(su);
;                     const f32x2 sp2 = {sp_, sp_}, su2 = {su, su}, v2 = {vi[h], vi[h]};
; #pragma unroll
;                     for (int j = 0; j < 8; ++j) { Pm[h][j] = __builtin_elementwise_fma(Pm[h][j], w[j], sp2 * b[j]);
;                         Um[h][j] = __builtin_elementwise_fma(Um[h][j], w[j], __builtin_elementwise_fma(su2, b[j], v2 * k[j])); }
;                 }
.LBB0_997:
	v_add_u32_e32 v95, s2, v137
	ds_read_b128 v[140:143], v95
	ds_read_b128 v[144:147], v95 offset:16
	ds_read_b128 v[148:151], v95 offset:32
	ds_read_b128 v[152:155], v95 offset:48
	ds_read_b128 v[156:159], v95 offset:256
	ds_read_b128 v[160:163], v95 offset:512
	ds_read_b128 v[164:167], v95 offset:768
	ds_read_b128 v[168:171], v95 offset:272
	ds_read_b128 v[172:175], v95 offset:528
	ds_read_b128 v[176:179], v95 offset:784
	ds_read_b128 v[180:183], v95 offset:288
	ds_read_b128 v[184:187], v95 offset:544
	ds_read_b128 v[188:191], v95 offset:800
	ds_read_b128 v[192:195], v95 offset:304
	ds_read_b128 v[198:201], v95 offset:560
	ds_read_b128 v[202:205], v95 offset:816
	s_waitcnt lgkmcnt(11)
	v_pk_fma_f32 v[208:209], v[88:89], v[156:157], 0 op_sel_hi:[1,1,0]
	v_pk_fma_f32 v[210:211], v[80:81], v[156:157], 0 op_sel_hi:[1,1,0]
	v_pk_fma_f32 v[208:209], v[90:91], v[158:159], v[208:209]
	v_pk_fma_f32 v[210:211], v[82:83], v[158:159], v[210:211]
	s_waitcnt lgkmcnt(8)
	v_pk_fma_f32 v[208:209], v[84:85], v[168:169], v[208:209]
	v_pk_fma_f32 v[210:211], v[72:73], v[168:169], v[210:211]
	v_pk_fma_f32 v[208:209], v[86:87], v[170:171], v[208:209]
	v_pk_fma_f32 v[210:211], v[74:75], v[170:171], v[210:211]
	s_waitcnt lgkmcnt(5)
	v_pk_fma_f32 v[208:209], v[76:77], v[180:181], v[208:209]
	v_pk_fma_f32 v[210:211], v[60:61], v[180:181], v[210:211]
	v_pk_fma_f32 v[208:209], v[78:79], v[182:183], v[208:209]
	v_add_u32_e32 v135, s2, v138
	v_pk_fma_f32 v[210:211], v[62:63], v[182:183], v[210:211]
	s_waitcnt lgkmcnt(2)
	v_pk_fma_f32 v[208:209], v[68:69], v[192:193], v[208:209]
	ds_read2_b32 v[206:207], v135 offset1:1
	v_pk_fma_f32 v[210:211], v[52:53], v[192:193], v[210:211]
	v_pk_fma_f32 v[208:209], v[70:71], v[194:195], v[208:209]
	v_pk_fma_f32 v[210:211], v[54:55], v[194:195], v[210:211]
	v_add_f32_e32 v208, v208, v209
	v_add_f32_e32 v209, v210, v211
	s_addk_i32 s2, 0xc00
	v_add_f32_dpp v208, v208, v208 quad_perm:[1,0,3,2] row_mask:0xf bank_mask:0xf bound_ctrl:1
	v_add_f32_dpp v209, v209, v209 quad_perm:[1,0,3,2] row_mask:0xf bank_mask:0xf bound_ctrl:1
	s_cmpk_eq_i32 s2, 0x6000
	v_add_f32_dpp v208, v208, v208 quad_perm:[2,3,0,1] row_mask:0xf bank_mask:0xf bound_ctrl:1
	v_pk_mul_f32 v[212:213], v[160:161], v[208:209] op_sel_hi:[1,0]
	v_add_f32_dpp v210, v209, v209 quad_perm:[2,3,0,1] row_mask:0xf bank_mask:0xf bound_ctrl:1
	v_pk_fma_f32 v[88:89], v[88:89], v[140:141], v[212:213]
	s_waitcnt lgkmcnt(0)
	v_pk_mul_f32 v[212:213], v[164:165], v[206:207] op_sel_hi:[1,0]
	v_pk_fma_f32 v[212:213], v[210:211], v[160:161], v[212:213] op_sel_hi:[0,1,1]
	v_pk_fma_f32 v[80:81], v[80:81], v[140:141], v[212:213]
	v_pk_mul_f32 v[212:213], v[162:163], v[208:209] op_sel_hi:[1,0]
	v_pk_fma_f32 v[90:91], v[90:91], v[142:143], v[212:213]
	v_pk_mul_f32 v[212:213], v[166:167], v[206:207] op_sel_hi:[1,0]
	v_pk_fma_f32 v[212:213], v[210:211], v[162:163], v[212:213] op_sel_hi:[0,1,1]
	v_pk_fma_f32 v[82:83], v[82:83], v[142:143], v[212:213]
	v_pk_mul_f32 v[212:213], v[172:173], v[208:209] op_sel_hi:[1,0]
	v_pk_fma_f32 v[84:85], v[84:85], v[144:145], v[212:213]
	v_pk_mul_f32 v[212:213], v[176:177], v[206:207] op_sel_hi:[1,0]
	v_pk_fma_f32 v[212:213], v[210:211], v[172:173], v[212:213] op_sel_hi:[0,1,1]
	v_pk_fma_f32 v[72:73], v[72:73], v[144:145], v[212:213]
	v_pk_mul_f32 v[212:213], v[174:175], v[208:209] op_sel_hi:[1,0]
	v_pk_fma_f32 v[86:87], v[86:87], v[146:147], v[212:213]
	v_pk_mul_f32 v[212:213], v[178:179], v[206:207] op_sel_hi:[1,0]
	v_pk_fma_f32 v[212:213], v[210:211], v[174:175], v[212:213] op_sel_hi:[0,1,1]
	v_pk_fma_f32 v[74:75], v[74:75], v[146:147], v[212:213]
	v_pk_mul_f32 v[212:213], v[184:185], v[208:209] op_sel_hi:[1,0]
	v_pk_fma_f32 v[76:77], v[76:77], v[148:149], v[212:213]
	v_pk_mul_f32 v[212:213], v[188:189], v[206:207] op_sel_hi:[1,0]
	v_pk_fma_f32 v[212:213], v[210:211], v[184:185], v[212:213] op_sel_hi:[0,1,1]
	v_pk_fma_f32 v[60:61], v[60:61], v[148:149], v[212:213]
	v_pk_mul_f32 v[212:213], v[186:187], v[208:209] op_sel_hi:[1,0]
	v_pk_fma_f32 v[78:79], v[78:79], v[150:151], v[212:213]
	v_pk_mul_f32 v[212:213], v[190:191], v[206:207] op_sel_hi:[1,0]
	v_pk_fma_f32 v[212:213], v[210:211], v[186:187], v[212:213] op_sel_hi:[0,1,1]
	v_pk_fma_f32 v[62:63], v[62:63], v[150:151], v[212:213]
	v_pk_mul_f32 v[212:213], v[198:199], v[208:209] op_sel_hi:[1,0]
	v_pk_mul_f32 v[208:209], v[200:201], v[208:209] op_sel_hi:[1,0]
	v_pk_fma_f32 v[68:69], v[68:69], v[152:153], v[212:213]
	v_pk_fma_f32 v[70:71], v[70:71], v[154:155], v[208:209]
	v_pk_mul_f32 v[208:209], v[204:205], v[206:207] op_sel_hi:[1,0]
	v_pk_mul_f32 v[212:213], v[202:203], v[206:207] op_sel_hi:[1,0]
	v_pk_fma_f32 v[208:209], v[210:211], v[200:201], v[208:209] op_sel_hi:[0,1,1]
	v_pk_fma_f32 v[54:55], v[54:55], v[154:155], v[208:209]
	v_pk_fma_f32 v[208:209], v[64:65], v[156:157], 0 op_sel_hi:[1,1,0]
	v_pk_fma_f32 v[156:157], v[40:41], v[156:157], 0 op_sel_hi:[1,1,0]
	v_pk_fma_f32 v[208:209], v[66:67], v[158:159], v[208:209]
	v_pk_fma_f32 v[156:157], v[42:43], v[158:159], v[156:157]
	v_pk_fma_f32 v[158:159], v[56:57], v[168:169], v[208:209]
	v_pk_fma_f32 v[156:157], v[36:37], v[168:169], v[156:157]
	v_pk_fma_f32 v[158:159], v[58:59], v[170:171], v[158:159]
	v_pk_fma_f32 v[156:157], v[38:39], v[170:171], v[156:157]
	v_pk_fma_f32 v[158:159], v[48:49], v[180:181], v[158:159]
	v_pk_fma_f32 v[156:157], v[28:29], v[180:181], v[156:157]
	v_pk_fma_f32 v[158:159], v[50:51], v[182:183], v[158:159]
	v_pk_fma_f32 v[156:157], v[30:31], v[182:183], v[156:157]
	v_pk_fma_f32 v[158:159], v[44:45], v[192:193], v[158:159]
	v_pk_fma_f32 v[156:157], v[32:33], v[192:193], v[156:157]
	v_pk_fma_f32 v[158:159], v[46:47], v[194:195], v[158:159]
; #define LAS __attribute__((address_space(3)))
; DEVI float dpp_xor1(float v) { return __int_as_float(__builtin_amdgcn_update_dpp(0, __float_as_int(v), 0xB1, 0xF, 0xF, false)); }
; DEVI float dpp_xor2(float v) { return __int_as_float(__builtin_amdgcn_update_dpp(0, __float_as_int(v), 0x4E, 0xF, 0xF, false)); }
; DEVI void rwkv_A(LAS unsigned char* lds, const Params& P) {
;     ...
;             for (int s = 0; s < RW_T; ++s) {
;                 const LAS unsigned char* sp = sb + s * RW_STEPB;
;                 f32x2 w[8], a[8], b[8], k[8];
; #pragma unroll
;                 for (int q = 0; q < 4; ++q) {
;                     const f32x4 tw = *(const LAS f32x4*)(sp + q * 16), ta = *(const LAS f32x4*)(sp + 256 + q * 16), tb_ = *(const LAS f32x4*)(sp + 512 + q * 16), tk = *(const LAS f32x4*)(sp + 768 + q * 16);
;                     w[2 * q] = (f32x2){tw[0], tw[1]}; w[2 * q + 1] = (f32x2){tw[2], tw[3]}; a[2 * q] = (f32x2){ta[0], ta[1]}; a[2 * q + 1] = (f32x2){ta[2], ta[3]};
;                     b[2 * q] = (f32x2){tb_[0], tb_[1]}; b[2 * q + 1] = (f32x2){tb_[2], tb_[3]}; k[2 * q] = (f32x2){tk[0], tk[1]}; k[2 * q + 1] = (f32x2){tk[2], tk[3]};
;                 }
;                 const LAS float* vp = (const LAS float*)(sp - qc * 64 + 1280 + rp * 8);
;                 const float vi[2] = {vp[0], vp[1]};
; #pragma unroll
;                 for (int h = 0; h < 2; ++h) {
;                     f32x2 ap = {0.f, 0.f}, au = {0.f, 0.f};
; #pragma unroll
;                     for (int j = 0; j < 8; ++j) { ap = __builtin_elementwise_fma(Pm[h][j], a[j], ap); au = __builtin_elementwise_fma(Um[h][j], a[j], au); }
;                     float sp_ = ap[0] + ap[1], su = au[0] + au[1];
;                     sp_ += dpp_xor1(sp_); su += dpp_xor1(su); sp_ += dpp_xor2(sp_); su += dpp_xor2(su);
;                     const f32x2 sp2 = {sp_, sp_}, su2 = {su, su}, v2 = {vi[h], vi[h]};
; #pragma unroll
;                     for (int j = 0; j < 8; ++j) { Pm[h][j] = __builtin_elementwise_fma(Pm[h][j], w[j], sp2 * b[j]);
;                         Um[h][j] = __builtin_elementwise_fma(Um[h][j], w[j], __builtin_elementwise_fma(su2, b[j], v2 * k[j])); }
;                 }
	v_pk_fma_f32 v[156:157], v[34:35], v[194:195], v[156:157]
	v_add_f32_e32 v158, v158, v159
	v_add_f32_e32 v156, v156, v157
	v_pk_fma_f32 v[212:213], v[210:211], v[198:199], v[212:213] op_sel_hi:[0,1,1]
	v_add_f32_dpp v157, v158, v158 quad_perm:[1,0,3,2] row_mask:0xf bank_mask:0xf bound_ctrl:1
	v_add_f32_dpp v158, v156, v156 quad_perm:[1,0,3,2] row_mask:0xf bank_mask:0xf bound_ctrl:1
	v_pk_fma_f32 v[52:53], v[52:53], v[152:153], v[212:213]
	v_add_f32_dpp v156, v157, v157 quad_perm:[2,3,0,1] row_mask:0xf bank_mask:0xf bound_ctrl:1
	v_pk_mul_f32 v[168:169], v[160:161], v[156:157] op_sel_hi:[1,0]
	v_add_f32_dpp v158, v158, v158 quad_perm:[2,3,0,1] row_mask:0xf bank_mask:0xf bound_ctrl:1
	v_pk_fma_f32 v[180:181], v[64:65], v[140:141], v[168:169]
	v_pk_mul_f32 v[64:65], v[164:165], v[206:207] op_sel:[0,1]
	v_pk_fma_f32 v[64:65], v[158:159], v[160:161], v[64:65] op_sel_hi:[0,1,1]
	v_pk_fma_f32 v[182:183], v[40:41], v[140:141], v[64:65]
	v_pk_mul_f32 v[40:41], v[162:163], v[156:157] op_sel_hi:[1,0]
	v_pk_fma_f32 v[192:193], v[66:67], v[142:143], v[40:41]
	v_pk_mul_f32 v[40:41], v[166:167], v[206:207] op_sel:[0,1]
	v_pk_fma_f32 v[40:41], v[158:159], v[162:163], v[40:41] op_sel_hi:[0,1,1]
	v_pk_fma_f32 v[194:195], v[42:43], v[142:143], v[40:41]
	v_pk_mul_f32 v[40:41], v[172:173], v[156:157] op_sel_hi:[1,0]
	v_pk_fma_f32 v[208:209], v[56:57], v[144:145], v[40:41]
	v_pk_mul_f32 v[40:41], v[176:177], v[206:207] op_sel:[0,1]
	v_pk_fma_f32 v[40:41], v[158:159], v[172:173], v[40:41] op_sel_hi:[0,1,1]
	v_pk_fma_f32 v[172:173], v[36:37], v[144:145], v[40:41]
	v_pk_mul_f32 v[36:37], v[174:175], v[156:157] op_sel_hi:[1,0]
	v_pk_fma_f32 v[176:177], v[58:59], v[146:147], v[36:37]
	v_pk_mul_f32 v[36:37], v[178:179], v[206:207] op_sel:[0,1]
	v_pk_fma_f32 v[36:37], v[158:159], v[174:175], v[36:37] op_sel_hi:[0,1,1]
	v_pk_fma_f32 v[174:175], v[38:39], v[146:147], v[36:37]
	v_pk_mul_f32 v[36:37], v[184:185], v[156:157] op_sel_hi:[1,0]
	v_pk_fma_f32 v[178:179], v[48:49], v[148:149], v[36:37]
	v_pk_mul_f32 v[36:37], v[188:189], v[206:207] op_sel:[0,1]
	v_pk_fma_f32 v[36:37], v[158:159], v[184:185], v[36:37] op_sel_hi:[0,1,1]
	v_pk_fma_f32 v[184:185], v[28:29], v[148:149], v[36:37]
	v_pk_mul_f32 v[28:29], v[186:187], v[156:157] op_sel_hi:[1,0]
	v_pk_fma_f32 v[188:189], v[50:51], v[150:151], v[28:29]
	v_pk_mul_f32 v[28:29], v[190:191], v[206:207] op_sel:[0,1]
	v_pk_fma_f32 v[28:29], v[158:159], v[186:187], v[28:29] op_sel_hi:[0,1,1]
	v_pk_fma_f32 v[186:187], v[30:31], v[150:151], v[28:29]
	v_pk_mul_f32 v[28:29], v[198:199], v[156:157] op_sel_hi:[1,0]
	v_pk_fma_f32 v[190:191], v[44:45], v[152:153], v[28:29]
	v_pk_mul_f32 v[28:29], v[202:203], v[206:207] op_sel:[0,1]
	v_pk_fma_f32 v[28:29], v[158:159], v[198:199], v[28:29] op_sel_hi:[0,1,1]
	v_pk_fma_f32 v[198:199], v[32:33], v[152:153], v[28:29]
	v_pk_mul_f32 v[28:29], v[200:201], v[156:157] op_sel_hi:[1,0]
	v_pk_fma_f32 v[202:203], v[46:47], v[154:155], v[28:29]
	v_pk_mul_f32 v[28:29], v[204:205], v[206:207] op_sel:[0,1]
	v_pk_fma_f32 v[28:29], v[158:159], v[200:201], v[28:29] op_sel_hi:[0,1,1]
	v_pk_fma_f32 v[200:201], v[34:35], v[154:155], v[28:29]
	ds_read_b128 v[28:31], v95 offset:1536
	ds_read_b128 v[32:35], v95 offset:1792
	ds_read_b128 v[36:39], v95 offset:2048
	ds_read_b128 v[40:43], v95 offset:2304
	ds_read_b128 v[44:47], v95 offset:1552
	ds_read_b128 v[48:51], v95 offset:1808
	ds_read_b128 v[140:143], v95 offset:2064
	ds_read_b128 v[144:147], v95 offset:2320
	ds_read_b128 v[148:151], v95 offset:1568
	ds_read_b128 v[56:59], v95 offset:1824
	ds_read_b128 v[152:155], v95 offset:2080
	ds_read_b128 v[156:159], v95 offset:2336
	ds_read_b128 v[160:163], v95 offset:1584
	ds_read_b128 v[64:67], v95 offset:1840
	ds_read_b128 v[164:167], v95 offset:2096
	ds_read_b128 v[168:171], v95 offset:2352
	s_waitcnt lgkmcnt(14)
	v_pk_fma_f32 v[206:207], v[88:89], v[32:33], 0 op_sel_hi:[1,1,0]
	v_pk_fma_f32 v[210:211], v[80:81], v[32:33], 0 op_sel_hi:[1,1,0]
	v_pk_fma_f32 v[206:207], v[90:91], v[34:35], v[206:207]
	v_pk_fma_f32 v[210:211], v[82:83], v[34:35], v[210:211]
	s_waitcnt lgkmcnt(10)
	v_pk_fma_f32 v[206:207], v[84:85], v[48:49], v[206:207]
	v_pk_fma_f32 v[210:211], v[72:73], v[48:49], v[210:211]
	v_pk_fma_f32 v[206:207], v[86:87], v[50:51], v[206:207]
	v_pk_fma_f32 v[210:211], v[74:75], v[50:51], v[210:211]
	s_waitcnt lgkmcnt(6)
	v_pk_fma_f32 v[206:207], v[76:77], v[56:57], v[206:207]
	v_add_u32_e32 v95, 0x600, v135
	v_pk_fma_f32 v[206:207], v[78:79], v[58:59], v[206:207]
	v_pk_fma_f32 v[210:211], v[60:61], v[56:57], v[210:211]
	s_waitcnt lgkmcnt(2)
	v_pk_fma_f32 v[206:207], v[68:69], v[64:65], v[206:207]
	ds_read2_b32 v[204:205], v95 offset1:1
	v_pk_fma_f32 v[210:211], v[62:63], v[58:59], v[210:211]
	v_pk_fma_f32 v[206:207], v[70:71], v[66:67], v[206:207]
	v_pk_fma_f32 v[210:211], v[52:53], v[64:65], v[210:211]
	v_add_f32_e32 v95, v206, v207
	v_pk_fma_f32 v[210:211], v[54:55], v[66:67], v[210:211]
	s_nop 0
	v_add_f32_dpp v95, v95, v95 quad_perm:[1,0,3,2] row_mask:0xf bank_mask:0xf bound_ctrl:1
	v_add_f32_e32 v135, v210, v211
	s_nop 0
	v_add_f32_dpp v206, v95, v95 quad_perm:[2,3,0,1] row_mask:0xf bank_mask:0xf bound_ctrl:1
	v_add_f32_dpp v135, v135, v135 quad_perm:[1,0,3,2] row_mask:0xf bank_mask:0xf bound_ctrl:1
	v_pk_mul_f32 v[212:213], v[36:37], v[206:207] op_sel_hi:[1,0]
	s_nop 0
	v_add_f32_dpp v210, v135, v135 quad_perm:[2,3,0,1] row_mask:0xf bank_mask:0xf bound_ctrl:1
	v_pk_fma_f32 v[88:89], v[88:89], v[28:29], v[212:213]
	s_waitcnt lgkmcnt(0)
; #define LAS __attribute__((address_space(3)))
; DEVI float dpp_xor1(float v) { return __int_as_float(__builtin_amdgcn_update_dpp(0, __float_as_int(v), 0xB1, 0xF, 0xF, false)); }
; DEVI float dpp_xor2(float v) { return __int_as_float(__builtin_amdgcn_update_dpp(0, __float_as_int(v), 0x4E, 0xF, 0xF, false)); }
; DEVI void rwkv_A(LAS unsigned char* lds, const Params& P) {
;     ...
;             for (int s = 0; s < RW_T; ++s) {
;                 const LAS unsigned char* sp = sb + s * RW_STEPB;
;                 f32x2 w[8], a[8], b[8], k[8];
; #pragma unroll
;                 for (int q = 0; q < 4; ++q) {
;                     const f32x4 tw = *(const LAS f32x4*)(sp + q * 16), ta = *(const LAS f32x4*)(sp + 256 + q * 16), tb_ = *(const LAS f32x4*)(sp + 512 + q * 16), tk = *(const LAS f32x4*)(sp + 768 + q * 16);
;                     w[2 * q] = (f32x2){tw[0], tw[1]}; w[2 * q + 1] = (f32x2){tw[2], tw[3]}; a[2 * q] = (f32x2){ta[0], ta[1]}; a[2 * q + 1] = (f32x2){ta[2], ta[3]};
;                     b[2 * q] = (f32x2){tb_[0], tb_[1]}; b[2 * q + 1] = (f32x2){tb_[2], tb_[3]}; k[2 * q] = (f32x2){tk[0], tk[1]}; k[2 * q + 1] = (f32x2){tk[2], tk[3]};
;                 }
;                 const LAS float* vp = (const LAS float*)(sp - qc * 64 + 1280 + rp * 8);
;                 const float vi[2] = {vp[0], vp[1]};
; #pragma unroll
;                 for (int h = 0; h < 2; ++h) {
;                     f32x2 ap = {0.f, 0.f}, au = {0.f, 0.f};
; #pragma unroll
;                     for (int j = 0; j < 8; ++j) { ap = __builtin_elementwise_fma(Pm[h][j], a[j], ap); au = __builtin_elementwise_fma(Um[h][j], a[j], au); }
;                     float sp_ = ap[0] + ap[1], su = au[0] + au[1];
;                     sp_ += dpp_xor1(sp_); su += dpp_xor1(su); sp_ += dpp_xor2(sp_); su += dpp_xor2(su);
;                     const f32x2 sp2 = {sp_, sp_}, su2 = {su, su}, v2 = {vi[h], vi[h]};
; #pragma unroll
;                     for (int j = 0; j < 8; ++j) { Pm[h][j] = __builtin_elementwise_fma(Pm[h][j], w[j], sp2 * b[j]);
;                         Um[h][j] = __builtin_elementwise_fma(Um[h][j], w[j], __builtin_elementwise_fma(su2, b[j], v2 * k[j])); }
;                 }
	v_pk_mul_f32 v[212:213], v[40:41], v[204:205] op_sel_hi:[1,0]
	v_pk_fma_f32 v[212:213], v[210:211], v[36:37], v[212:213] op_sel_hi:[0,1,1]
	v_pk_fma_f32 v[80:81], v[80:81], v[28:29], v[212:213]
	v_pk_mul_f32 v[212:213], v[38:39], v[206:207] op_sel_hi:[1,0]
	v_pk_fma_f32 v[90:91], v[90:91], v[30:31], v[212:213]
	v_pk_mul_f32 v[212:213], v[42:43], v[204:205] op_sel_hi:[1,0]
	v_pk_fma_f32 v[212:213], v[210:211], v[38:39], v[212:213] op_sel_hi:[0,1,1]
	v_pk_fma_f32 v[82:83], v[82:83], v[30:31], v[212:213]
	v_pk_mul_f32 v[212:213], v[140:141], v[206:207] op_sel_hi:[1,0]
	v_pk_fma_f32 v[84:85], v[84:85], v[44:45], v[212:213]
	v_pk_mul_f32 v[212:213], v[144:145], v[204:205] op_sel_hi:[1,0]
	v_pk_fma_f32 v[212:213], v[210:211], v[140:141], v[212:213] op_sel_hi:[0,1,1]
	v_pk_fma_f32 v[72:73], v[72:73], v[44:45], v[212:213]
	v_pk_mul_f32 v[212:213], v[142:143], v[206:207] op_sel_hi:[1,0]
	v_pk_fma_f32 v[86:87], v[86:87], v[46:47], v[212:213]
	v_pk_mul_f32 v[212:213], v[146:147], v[204:205] op_sel_hi:[1,0]
	v_pk_fma_f32 v[212:213], v[210:211], v[142:143], v[212:213] op_sel_hi:[0,1,1]
	v_pk_fma_f32 v[74:75], v[74:75], v[46:47], v[212:213]
	v_pk_mul_f32 v[212:213], v[152:153], v[206:207] op_sel_hi:[1,0]
	v_pk_fma_f32 v[76:77], v[76:77], v[148:149], v[212:213]
	v_pk_mul_f32 v[212:213], v[156:157], v[204:205] op_sel_hi:[1,0]
	v_pk_fma_f32 v[212:213], v[210:211], v[152:153], v[212:213] op_sel_hi:[0,1,1]
	v_pk_fma_f32 v[60:61], v[60:61], v[148:149], v[212:213]
	v_pk_mul_f32 v[212:213], v[154:155], v[206:207] op_sel_hi:[1,0]
	v_pk_fma_f32 v[78:79], v[78:79], v[150:151], v[212:213]
	v_pk_mul_f32 v[212:213], v[158:159], v[204:205] op_sel_hi:[1,0]
	v_pk_fma_f32 v[212:213], v[210:211], v[154:155], v[212:213] op_sel_hi:[0,1,1]
	v_pk_fma_f32 v[62:63], v[62:63], v[150:151], v[212:213]
	v_pk_mul_f32 v[212:213], v[164:165], v[206:207] op_sel_hi:[1,0]
	v_pk_mul_f32 v[206:207], v[166:167], v[206:207] op_sel_hi:[1,0]
	v_pk_fma_f32 v[68:69], v[68:69], v[160:161], v[212:213]
	v_pk_fma_f32 v[70:71], v[70:71], v[162:163], v[206:207]
	v_pk_mul_f32 v[206:207], v[170:171], v[204:205] op_sel_hi:[1,0]
	v_pk_mul_f32 v[212:213], v[168:169], v[204:205] op_sel_hi:[1,0]
	v_pk_fma_f32 v[206:207], v[210:211], v[166:167], v[206:207] op_sel_hi:[0,1,1]
	v_pk_fma_f32 v[54:55], v[54:55], v[162:163], v[206:207]
	v_pk_fma_f32 v[206:207], v[180:181], v[32:33], 0 op_sel_hi:[1,1,0]
	v_pk_fma_f32 v[32:33], v[182:183], v[32:33], 0 op_sel_hi:[1,1,0]
	v_pk_fma_f32 v[206:207], v[192:193], v[34:35], v[206:207]
	v_pk_fma_f32 v[32:33], v[194:195], v[34:35], v[32:33]
	v_pk_fma_f32 v[34:35], v[208:209], v[48:49], v[206:207]
	v_pk_fma_f32 v[32:33], v[172:173], v[48:49], v[32:33]
	v_pk_fma_f32 v[34:35], v[176:177], v[50:51], v[34:35]
	v_pk_fma_f32 v[32:33], v[174:175], v[50:51], v[32:33]
	v_pk_fma_f32 v[34:35], v[178:179], v[56:57], v[34:35]
	v_pk_fma_f32 v[32:33], v[184:185], v[56:57], v[32:33]
	v_pk_fma_f32 v[34:35], v[188:189], v[58:59], v[34:35]
	v_pk_fma_f32 v[32:33], v[186:187], v[58:59], v[32:33]
	v_pk_fma_f32 v[34:35], v[190:191], v[64:65], v[34:35]
	v_pk_fma_f32 v[32:33], v[198:199], v[64:65], v[32:33]
	v_pk_fma_f32 v[34:35], v[202:203], v[66:67], v[34:35]
	v_pk_fma_f32 v[32:33], v[200:201], v[66:67], v[32:33]
	v_add_f32_e32 v34, v34, v35
	v_add_f32_e32 v32, v32, v33
	v_pk_fma_f32 v[212:213], v[210:211], v[164:165], v[212:213] op_sel_hi:[0,1,1]
	v_add_f32_dpp v33, v34, v34 quad_perm:[1,0,3,2] row_mask:0xf bank_mask:0xf bound_ctrl:1
	v_add_f32_dpp v32, v32, v32 quad_perm:[1,0,3,2] row_mask:0xf bank_mask:0xf bound_ctrl:1
	v_pk_fma_f32 v[52:53], v[52:53], v[160:161], v[212:213]
	v_add_f32_dpp v34, v33, v33 quad_perm:[2,3,0,1] row_mask:0xf bank_mask:0xf bound_ctrl:1
	v_add_f32_dpp v206, v32, v32 quad_perm:[2,3,0,1] row_mask:0xf bank_mask:0xf bound_ctrl:1
	v_pk_mul_f32 v[32:33], v[36:37], v[34:35] op_sel_hi:[1,0]
	v_pk_fma_f32 v[64:65], v[180:181], v[28:29], v[32:33]
	v_pk_mul_f32 v[32:33], v[40:41], v[204:205] op_sel:[0,1]
	v_pk_fma_f32 v[32:33], v[206:207], v[36:37], v[32:33] op_sel_hi:[0,1,1]
	v_pk_fma_f32 v[40:41], v[182:183], v[28:29], v[32:33]
	v_pk_mul_f32 v[28:29], v[38:39], v[34:35] op_sel_hi:[1,0]
	v_pk_mul_f32 v[32:33], v[164:165], v[34:35] op_sel_hi:[1,0]
	v_pk_fma_f32 v[66:67], v[192:193], v[30:31], v[28:29]
	v_pk_mul_f32 v[28:29], v[42:43], v[204:205] op_sel:[0,1]
	v_pk_fma_f32 v[28:29], v[206:207], v[38:39], v[28:29] op_sel_hi:[0,1,1]
	v_pk_fma_f32 v[42:43], v[194:195], v[30:31], v[28:29]
	v_pk_mul_f32 v[28:29], v[140:141], v[34:35] op_sel_hi:[1,0]
	v_pk_mul_f32 v[30:31], v[154:155], v[34:35] op_sel_hi:[1,0]
	v_pk_fma_f32 v[56:57], v[208:209], v[44:45], v[28:29]
	v_pk_mul_f32 v[28:29], v[144:145], v[204:205] op_sel:[0,1]
	v_pk_fma_f32 v[50:51], v[188:189], v[150:151], v[30:31]
	v_pk_fma_f32 v[28:29], v[206:207], v[140:141], v[28:29] op_sel_hi:[0,1,1]
	v_pk_fma_f32 v[36:37], v[172:173], v[44:45], v[28:29]
	v_pk_mul_f32 v[28:29], v[142:143], v[34:35] op_sel_hi:[1,0]
	v_pk_mul_f32 v[30:31], v[158:159], v[204:205] op_sel:[0,1]
	v_pk_fma_f32 v[58:59], v[176:177], v[46:47], v[28:29]
	v_pk_mul_f32 v[28:29], v[146:147], v[204:205] op_sel:[0,1]
	v_pk_fma_f32 v[44:45], v[190:191], v[160:161], v[32:33]
	v_pk_fma_f32 v[28:29], v[206:207], v[142:143], v[28:29] op_sel_hi:[0,1,1]
	v_pk_fma_f32 v[38:39], v[174:175], v[46:47], v[28:29]
	v_pk_mul_f32 v[28:29], v[152:153], v[34:35] op_sel_hi:[1,0]
	v_pk_mul_f32 v[34:35], v[166:167], v[34:35] op_sel_hi:[1,0]
	v_pk_fma_f32 v[48:49], v[178:179], v[148:149], v[28:29]
	v_pk_mul_f32 v[28:29], v[156:157], v[204:205] op_sel:[0,1]
	v_pk_mul_f32 v[32:33], v[168:169], v[204:205] op_sel:[0,1]
	v_pk_fma_f32 v[46:47], v[202:203], v[162:163], v[34:35]
	v_pk_mul_f32 v[34:35], v[170:171], v[204:205] op_sel:[0,1]
	v_pk_fma_f32 v[28:29], v[206:207], v[152:153], v[28:29] op_sel_hi:[0,1,1]
	v_pk_fma_f32 v[30:31], v[206:207], v[154:155], v[30:31] op_sel_hi:[0,1,1]
	v_pk_fma_f32 v[32:33], v[206:207], v[164:165], v[32:33] op_sel_hi:[0,1,1]
	v_pk_fma_f32 v[34:35], v[206:207], v[166:167], v[34:35] op_sel_hi:[0,1,1]
	v_pk_fma_f32 v[28:29], v[184:185], v[148:149], v[28:29]
	v_pk_fma_f32 v[30:31], v[186:187], v[150:151], v[30:31]
	v_pk_fma_f32 v[32:33], v[198:199], v[160:161], v[32:33]
	v_pk_fma_f32 v[34:35], v[200:201], v[162:163], v[34:35]
	s_cbranch_scc0 .LBB0_997
; DEVI void rwkv_A(LAS unsigned char* lds, const Params& P) {
;     ...
;             __syncthreads();
;         }
; #pragma unroll
;         for (int h = 0; h < 2; ++h) {
;             float* po = pu + ((size_t)item * 2) * 4096 + (2 * rp + h) * 64 + qc * 16;
; #pragma unroll
;             for (int q = 0; q < 4; ++q) { *(f32x4*)(po + q * 4) = (f32x4){Pm[h][2 * q][0], Pm[h][2 * q][1], Pm[h][2 * q + 1][0], Pm[h][2 * q + 1][1]};
;                 *(f32x4*)(po + 4096 + q * 4) = (f32x4){Um[h][2 * q][0], Um[h][2 * q][1], Um[h][2 * q + 1][0], Um[h][2 * q + 1][1]}; }
;         }
	s_cmp_eq_u32 s1, 16
	s_barrier
	s_cbranch_scc0 .LBB0_994
	s_waitcnt vmcnt(6)
	v_lshlrev_b64 v[0:1], 15, v[130:131]
	v_lshl_add_u64 v[0:1], v[128:129], 0, v[0:1]
	v_add_co_u32_e32 v2, vcc, 0x4000, v0
	s_add_i32 s0, s0, s48
	s_nop 0
	v_addc_co_u32_e32 v3, vcc, 0, v1, vcc
	s_cmpk_gt_i32 s0, 0x3ff
	global_store_dwordx4 v[0:1], v[88:91], off
	global_store_dwordx4 v[2:3], v[80:83], off
	global_store_dwordx4 v[0:1], v[84:87], off offset:16
	global_store_dwordx4 v[2:3], v[72:75], off offset:16
	global_store_dwordx4 v[0:1], v[76:79], off offset:32
	global_store_dwordx4 v[2:3], v[60:63], off offset:32
	global_store_dwordx4 v[0:1], v[68:71], off offset:48
	global_store_dwordx4 v[2:3], v[52:55], off offset:48
	global_store_dwordx4 v[0:1], v[64:67], off offset:256
	global_store_dwordx4 v[2:3], v[40:43], off offset:256
	global_store_dwordx4 v[0:1], v[56:59], off offset:272
	global_store_dwordx4 v[2:3], v[36:39], off offset:272
	global_store_dwordx4 v[0:1], v[48:51], off offset:288
	global_store_dwordx4 v[2:3], v[28:31], off offset:288
	global_store_dwordx4 v[0:1], v[44:47], off offset:304
	global_store_dwordx4 v[2:3], v[32:35], off offset:304
	s_cbranch_scc0 .LBB0_993

; DEVI unsigned pk_bf16(float lo, float hi) { unsigned r; asm("v_cvt_pk_bf16_f32 %0, %1, %2" : "=v"(r) : "v"(lo), "v"(hi)); return r; }
; template <int DQK, int MODE>
; DEVI void attn_item(LAS unsigned char* lds, const bf16_t* Qh, int qs, const bf16_t* Kh, int ks_, const bf16_t* Vh, int vs, bf16_t* Oh, int os,
;                     float* lse, int lses, int i0, int dil, int res) {
;     ...
;             float mx = s0[0];
; #pragma unroll
;             for (int j = 0; j < 16; ++j) asm("v_max3_f32 %0, %0, %1, %2" : "+v"(mx) : "v"(s0[j]), "v"(s1[j]));
;             { const u32x2 sw = __builtin_amdgcn_permlane32_swap(__float_as_uint(mx), __float_as_uint(mx), false, false);
;               mx = fmaxf(__uint_as_float(sw[0]), __uint_as_float(sw[1])); }
;             const float mnew = fmaxf(mrun, mx);
;             const float alpha = __builtin_amdgcn_exp2f(mrun - mnew);
;             mrun = mnew;
;             const float msafe = fmaxf(mnew, -1e29f);
;             float ls = 0.f;
; #pragma unroll
;             for (int j = 0; j < 16; ++j) { const float p0 = __builtin_amdgcn_exp2f(s0[j] - msafe), p1 = __builtin_amdgcn_exp2f(s1[j] - msafe);
;                 s0[j] = p0; s1[j] = p1; ls += p0 + p1; }
;             lrun = lrun * alpha + ls;
; #pragma unroll
;             for (int c = 0; c < 4; ++c)
; #pragma unroll
;                 for (int j = 0; j < 16; ++j) O[c][j] *= alpha;
;             pk[0] = (u32x4){pk_bf16(s0[0], s0[1]), pk_bf16(s0[2], s0[3]), pk_bf16(s0[4], s0[5]), pk_bf16(s0[6], s0[7])};
;             pk[1] = (u32x4){pk_bf16(s0[8], s0[9]), pk_bf16(s0[10], s0[11]), pk_bf16(s0[12], s0[13]), pk_bf16(s0[14], s0[15])};
;             pk[2] = (u32x4){pk_bf16(s1[0], s1[1]), pk_bf16(s1[2], s1[3]), pk_bf16(s1[4], s1[5]), pk_bf16(s1[6], s1[7])};
;             pk[3] = (u32x4){pk_bf16(s1[8], s1[9]), pk_bf16(s1[10], s1[11]), pk_bf16(s1[12], s1[13]), pk_bf16(s1[14], s1[15])};
.LBB0_2224:
	s_or_b64 exec, exec, s[16:17]
	s_nop 2
	v_mov_b32_e32 v0, v96
	v_max3_f32 v0, v0, v96, v80
	s_andn2_b64 vcc, exec, s[66:67]
	v_max3_f32 v0, v0, v97, v81
	v_max3_f32 v0, v0, v98, v82
	v_max3_f32 v0, v0, v99, v83
	v_max3_f32 v0, v0, v100, v84
	v_max3_f32 v0, v0, v101, v85
	v_max3_f32 v0, v0, v102, v86
	v_max3_f32 v0, v0, v103, v87
	v_max3_f32 v0, v0, v104, v88
	v_max3_f32 v0, v0, v105, v89
	v_max3_f32 v0, v0, v106, v90
	v_max3_f32 v0, v0, v107, v91
	v_max3_f32 v0, v0, v108, v92
	v_max3_f32 v0, v0, v109, v93
	v_max3_f32 v0, v0, v110, v94
	v_max3_f32 v0, v0, v111, v95
	v_mov_b32_e32 v2, v0
	s_nop 1
	v_permlane32_swap_b32_e32 v0, v2
	v_max3_f32 v200, v170, v0, v2
	v_max_f32_e32 v202, 0xefa18f08, v200
	v_sub_f32_e32 v0, v96, v202
	v_sub_f32_e32 v10, v85, v202
	v_exp_f32_e32 v3, v0
	v_sub_f32_e32 v0, v80, v202
	v_sub_f32_e32 v4, v98, v202
	v_sub_f32_e32 v6, v83, v202
	v_exp_f32_e32 v12, v10
	v_sub_f32_e32 v10, v102, v202
	v_sub_f32_e32 v14, v87, v202
	v_sub_f32_e32 v80, v89, v202
	v_exp_f32_e32 v7, v4
	v_sub_f32_e32 v4, v82, v202
	v_exp_f32_e32 v8, v6
	v_sub_f32_e32 v6, v100, v202
	v_exp_f32_e32 v15, v10
	v_sub_f32_e32 v10, v86, v202
	v_exp_f32_e32 v96, v14
	v_sub_f32_e32 v14, v104, v202
	v_exp_f32_e32 v100, v80
	v_sub_f32_e32 v80, v106, v202
	v_exp_f32_e32 v5, v0
	v_sub_f32_e32 v0, v97, v202
	v_exp_f32_e32 v9, v4
	v_sub_f32_e32 v4, v99, v202
	v_exp_f32_e32 v11, v6
	v_sub_f32_e32 v6, v84, v202
	v_exp_f32_e32 v97, v10
	v_sub_f32_e32 v10, v103, v202
	v_exp_f32_e32 v99, v14
	v_sub_f32_e32 v14, v88, v202
	v_exp_f32_e32 v103, v80
	v_sub_f32_e32 v80, v90, v202
	v_exp_f32_e32 v13, v6
	v_sub_f32_e32 v6, v101, v202
	v_exp_f32_e32 v101, v14
	v_sub_f32_e32 v14, v105, v202
	v_exp_f32_e32 v105, v80
	v_sub_f32_e32 v80, v107, v202
	v_exp_f32_e32 v98, v80
	v_sub_f32_e32 v80, v91, v202
	v_exp_f32_e32 v104, v80
	v_sub_f32_e32 v80, v108, v202
	v_exp_f32_e32 v107, v80
	v_sub_f32_e32 v80, v92, v202
	v_exp_f32_e32 v171, v80
	v_sub_f32_e32 v80, v109, v202
	v_exp_f32_e32 v102, v80
	v_sub_f32_e32 v80, v93, v202
	v_exp_f32_e32 v108, v80
	v_sub_f32_e32 v80, v110, v202
	v_exp_f32_e32 v109, v80
	v_sub_f32_e32 v80, v94, v202
	v_sub_f32_e32 v170, v170, v200
	v_exp_f32_e32 v201, v80
	v_sub_f32_e32 v80, v111, v202
	v_exp_f32_e32 v2, v0
	v_sub_f32_e32 v0, v81, v202
	v_exp_f32_e32 v106, v170
	v_exp_f32_e32 v110, v80
	v_sub_f32_e32 v80, v95, v202
	v_exp_f32_e32 v0, v0
	v_exp_f32_e32 v4, v4
	v_exp_f32_e32 v6, v6
	v_exp_f32_e32 v10, v10
	v_exp_f32_e32 v14, v14
	v_exp_f32_e32 v170, v80
	v_pk_mul_f32 v[78:79], v[78:79], v[106:107] op_sel_hi:[1,0]
	v_pk_mul_f32 v[76:77], v[76:77], v[106:107] op_sel_hi:[1,0]
	v_pk_mul_f32 v[74:75], v[74:75], v[106:107] op_sel_hi:[1,0]
	v_pk_mul_f32 v[72:73], v[72:73], v[106:107] op_sel_hi:[1,0]
	v_pk_mul_f32 v[70:71], v[70:71], v[106:107] op_sel_hi:[1,0]
	v_pk_mul_f32 v[68:69], v[68:69], v[106:107] op_sel_hi:[1,0]
	v_pk_mul_f32 v[66:67], v[66:67], v[106:107] op_sel_hi:[1,0]
	v_pk_mul_f32 v[64:65], v[64:65], v[106:107] op_sel_hi:[1,0]
	v_pk_mul_f32 v[62:63], v[62:63], v[106:107] op_sel_hi:[1,0]
	v_pk_mul_f32 v[60:61], v[60:61], v[106:107] op_sel_hi:[1,0]
	v_pk_mul_f32 v[58:59], v[58:59], v[106:107] op_sel_hi:[1,0]
	v_pk_mul_f32 v[56:57], v[56:57], v[106:107] op_sel_hi:[1,0]
	v_pk_mul_f32 v[54:55], v[54:55], v[106:107] op_sel_hi:[1,0]
	v_pk_mul_f32 v[52:53], v[52:53], v[106:107] op_sel_hi:[1,0]
	v_pk_mul_f32 v[50:51], v[50:51], v[106:107] op_sel_hi:[1,0]
	v_pk_mul_f32 v[48:49], v[48:49], v[106:107] op_sel_hi:[1,0]
	v_pk_mul_f32 v[46:47], v[46:47], v[106:107] op_sel_hi:[1,0]
	v_pk_mul_f32 v[44:45], v[44:45], v[106:107] op_sel_hi:[1,0]
	v_pk_mul_f32 v[42:43], v[42:43], v[106:107] op_sel_hi:[1,0]
	v_pk_mul_f32 v[40:41], v[40:41], v[106:107] op_sel_hi:[1,0]
	v_pk_mul_f32 v[38:39], v[38:39], v[106:107] op_sel_hi:[1,0]
	v_pk_mul_f32 v[36:37], v[36:37], v[106:107] op_sel_hi:[1,0]
	v_pk_mul_f32 v[34:35], v[34:35], v[106:107] op_sel_hi:[1,0]
	v_pk_mul_f32 v[32:33], v[32:33], v[106:107] op_sel_hi:[1,0]
	v_pk_mul_f32 v[30:31], v[30:31], v[106:107] op_sel_hi:[1,0]
	v_pk_mul_f32 v[28:29], v[28:29], v[106:107] op_sel_hi:[1,0]
	v_pk_mul_f32 v[26:27], v[26:27], v[106:107] op_sel_hi:[1,0]
	v_pk_mul_f32 v[24:25], v[24:25], v[106:107] op_sel_hi:[1,0]
	v_pk_mul_f32 v[22:23], v[22:23], v[106:107] op_sel_hi:[1,0]
	v_pk_mul_f32 v[20:21], v[20:21], v[106:107] op_sel_hi:[1,0]
	v_pk_mul_f32 v[18:19], v[18:19], v[106:107] op_sel_hi:[1,0]
	v_pk_mul_f32 v[16:17], v[16:17], v[106:107] op_sel_hi:[1,0]
	v_cvt_pk_bf16_f32 v92, v3, v2
	v_cvt_pk_bf16_f32 v93, v7, v4
	v_cvt_pk_bf16_f32 v94, v11, v6
	v_cvt_pk_bf16_f32 v95, v15, v10
	v_cvt_pk_bf16_f32 v88, v99, v14
	v_cvt_pk_bf16_f32 v89, v103, v98
	v_cvt_pk_bf16_f32 v90, v107, v102
	v_cvt_pk_bf16_f32 v91, v109, v110
	v_cvt_pk_bf16_f32 v84, v5, v0
	v_cvt_pk_bf16_f32 v85, v9, v8
	v_cvt_pk_bf16_f32 v86, v13, v12
	v_cvt_pk_bf16_f32 v87, v97, v96
	v_cvt_pk_bf16_f32 v80, v101, v100
	v_cvt_pk_bf16_f32 v81, v105, v104
	v_cvt_pk_bf16_f32 v82, v171, v108
	v_cvt_pk_bf16_f32 v83, v201, v170
	s_cbranch_vccnz .LBB0_2226
; #define LAS __attribute__((address_space(3)))
; template <int DQK, int MODE>
; DEVI void attn_item(LAS unsigned char* lds, const bf16_t* Qh, int qs, const bf16_t* Kh, int ks_, const bf16_t* Vh, int vs, bf16_t* Oh, int os,
;                     float* lse, int lses, int i0, int dil, int res) {
;     ...
;     auto pv = [&](int vbi) {
;         const LAS unsigned char* vbuf = lds + C::VOFF + vbi * C::VB + (4 * hh + vq) * C::VSTR + (16 * vblk + 4 * vp) * 2;
;         auto vld = [&](int i) {
;             const int sl = i >> 2, c = i & 3;
;             const LAS unsigned char* a = vbuf + (32 * (sl >> 1) + 16 * (sl & 1)) * C::VSTR + 64 * c;
;             const s16x4 t0 = __builtin_amdgcn_ds_read_tr16_b64_v4i16((LAS s16x4*)a);
;             const s16x4 t1 = __builtin_amdgcn_ds_read_tr16_b64_v4i16((LAS s16x4*)(a + 8 * C::VSTR));
;             bf16x8 vf; vf[0] = t0[0]; vf[1] = t0[1]; vf[2] = t0[2]; vf[3] = t0[3]; vf[4] = t1[0]; vf[5] = t1[1]; vf[6] = t1[2]; vf[7] = t1[3];
;             return vf;
;         };
;         bf16x8 fv[3];
;         __builtin_amdgcn_s_setprio(1);
;         fv[0] = vld(0); fv[1] = vld(1);
;         __builtin_amdgcn_sched_barrier(0);
; #pragma unroll
;         for (int i = 0; i < 16; ++i) {
;             if (i + 2 < 16) fv[(i + 2) % 3] = vld(i + 2);
;             __builtin_amdgcn_sched_barrier(0);
;             bf16x8 pf; __builtin_memcpy(&pf, &pk[i >> 2], 16);
;             O[i & 3] = __builtin_amdgcn_mfma_f32_32x32x16_bf16(fv[i % 3], pf, O[i & 3], 0, 0, 0);
;             __builtin_amdgcn_sched_barrier(0);
;         }
;         __builtin_amdgcn_s_setprio(0);
;     };
	s_mul_i32 s16, s63, 0x5000
	v_add_u32_e32 v111, s16, v185
	s_setprio 1
	ds_read_b64_tr_b16 v[202:203], v111 offset:34816
	ds_read_b64_tr_b16 v[204:205], v111 offset:37376
	ds_read_b64_tr_b16 v[208:209], v111 offset:37440
	ds_read_b64_tr_b16 v[206:207], v111 offset:34880
	ds_read_b64_tr_b16 v[210:211], v111 offset:34944
	ds_read_b64_tr_b16 v[212:213], v111 offset:37504
	s_waitcnt lgkmcnt(4)
	v_mfma_f32_32x32x16_bf16 v[64:79], v[202:205], v[92:95], v[64:79]
	ds_read_b64_tr_b16 v[202:203], v111 offset:35008
	ds_read_b64_tr_b16 v[204:205], v111 offset:37568
	s_waitcnt lgkmcnt(4)
	v_mfma_f32_32x32x16_bf16 v[48:63], v[206:209], v[92:95], v[48:63]
	ds_read_b64_tr_b16 v[206:207], v111 offset:39936
	ds_read_b64_tr_b16 v[208:209], v111 offset:42496
	s_waitcnt lgkmcnt(4)
	v_mfma_f32_32x32x16_bf16 v[32:47], v[210:213], v[92:95], v[32:47]
	ds_read_b64_tr_b16 v[210:211], v111 offset:40000
	ds_read_b64_tr_b16 v[212:213], v111 offset:42560
	s_waitcnt lgkmcnt(4)
	v_mfma_f32_32x32x16_bf16 v[16:31], v[202:205], v[92:95], v[16:31]
	ds_read_b64_tr_b16 v[202:203], v111 offset:40064
	ds_read_b64_tr_b16 v[204:205], v111 offset:42624
	s_waitcnt lgkmcnt(4)
	v_mfma_f32_32x32x16_bf16 v[64:79], v[206:209], v[88:91], v[64:79]
	ds_read_b64_tr_b16 v[206:207], v111 offset:40128
	ds_read_b64_tr_b16 v[208:209], v111 offset:42688
	s_waitcnt lgkmcnt(4)
	v_mfma_f32_32x32x16_bf16 v[48:63], v[210:213], v[88:91], v[48:63]
	ds_read_b64_tr_b16 v[210:211], v111 offset:45056
	ds_read_b64_tr_b16 v[212:213], v111 offset:47616
	s_waitcnt lgkmcnt(4)
	v_mfma_f32_32x32x16_bf16 v[32:47], v[202:205], v[88:91], v[32:47]
	ds_read_b64_tr_b16 v[202:203], v111 offset:45120
	ds_read_b64_tr_b16 v[204:205], v111 offset:47680
	s_waitcnt lgkmcnt(4)
	v_mfma_f32_32x32x16_bf16 v[16:31], v[206:209], v[88:91], v[16:31]
	ds_read_b64_tr_b16 v[206:207], v111 offset:45184
	ds_read_b64_tr_b16 v[208:209], v111 offset:47744
	s_waitcnt lgkmcnt(4)
	v_mfma_f32_32x32x16_bf16 v[64:79], v[210:213], v[84:87], v[64:79]
	ds_read_b64_tr_b16 v[210:211], v111 offset:45248
	ds_read_b64_tr_b16 v[212:213], v111 offset:47808
	s_waitcnt lgkmcnt(4)
	v_mfma_f32_32x32x16_bf16 v[48:63], v[202:205], v[84:87], v[48:63]
	ds_read_b64_tr_b16 v[202:203], v111 offset:50176
	ds_read_b64_tr_b16 v[204:205], v111 offset:52736
	s_waitcnt lgkmcnt(4)
	v_mfma_f32_32x32x16_bf16 v[32:47], v[206:209], v[84:87], v[32:47]
	ds_read_b64_tr_b16 v[206:207], v111 offset:50240
	ds_read_b64_tr_b16 v[208:209], v111 offset:52800
	s_waitcnt lgkmcnt(4)
	v_mfma_f32_32x32x16_bf16 v[16:31], v[210:213], v[84:87], v[16:31]
	ds_read_b64_tr_b16 v[210:211], v111 offset:50304
	ds_read_b64_tr_b16 v[212:213], v111 offset:52864
	s_waitcnt lgkmcnt(4)
	v_mfma_f32_32x32x16_bf16 v[64:79], v[202:205], v[80:83], v[64:79]
	ds_read_b64_tr_b16 v[202:203], v111 offset:50368
	ds_read_b64_tr_b16 v[204:205], v111 offset:52928
	s_waitcnt lgkmcnt(4)
	v_mfma_f32_32x32x16_bf16 v[48:63], v[206:209], v[80:83], v[48:63]
	s_waitcnt lgkmcnt(2)
	v_mfma_f32_32x32x16_bf16 v[32:47], v[210:213], v[80:83], v[32:47]
	s_waitcnt lgkmcnt(0)
	v_mfma_f32_32x32x16_bf16 v[16:31], v[202:205], v[80:83], v[16:31]
	s_setprio 0
	s_mov_b64 s[16:17], 0
	s_branch .LBB0_2227
